# GEMM M-segment: removed the s_setprio 0/1 pair between the two MFMA blocks (32 MFMAs issue uninterrupted)
# baseline (speedup 1.0000x reference)
; #define PG8_STAGE(bufoff, gbase, voff) do { _Pragma("unroll") for (int _i = 0; _i < 2; ++_i) \
;         __builtin_amdgcn_global_load_lds((const unsigned*)((const char*)(gbase) + (voff)[_i]), (PG8_LAS unsigned*)(lds + (bufoff) + ldsw + _i * 8192), 16, 0, 0); } while (0)
; #define PG8_LDA(dst, b, h) do { _Pragma("unroll") for (int m = 0; m < 4; ++m) _Pragma("unroll") for (int k = 0; k < 2; ++k) dst[m][k] = *(const PG8_LAS bf16x8*)(lds + PG8_SA(b, h) + aoff + m * 2048 + k * 1024); } while (0)
; #define PG8_LDB(dst, b, h) do { _Pragma("unroll") for (int n = 0; n < 2; ++n) _Pragma("unroll") for (int k = 0; k < 2; ++k) dst[n][k] = *(const PG8_LAS bf16x8*)(lds + PG8_SB(b, h) + boff + n * 2048 + k * 1024); } while (0)
; #define PG8_WAIT_V(n) asm volatile("s_waitcnt vmcnt(" #n ")" ::: "memory")
; #define PG8_WAIT_L(n) asm volatile("s_waitcnt lgkmcnt(" #n ")" ::: "memory")
; #define PG8_BAR __builtin_amdgcn_s_barrier()
; #define PG8_SCHED __builtin_amdgcn_sched_barrier(0)
; template <class Epi, class Sched, bool ALIGN_EPI = false, bool SP2 = false>
; __device__ __forceinline__ void gemm_phase(PG8_LAS unsigned char* lds, const Gemm g, const Sched& S, const Epi& E) {
;     ...
;         const char* nA = has_next ? (const char*)g.A + (size_t)nxt.pm * tstep : cA; const char* nB = has_next ? (const char*)g.Bt + (size_t)nxt.pn * tstep : cB;
;         for (int t = 0; t < nt; t += 2) {
;             const bool last = (t == nt - 2);
;             const char* a1 = cA + (size_t)(t + 1) * kstepB;
;             const char* a2 = last ? nA : cA + (size_t)(t + 2) * kstepB; const char* b2 = last ? nB : cB + (size_t)(t + 2) * kstepB;
;             const char* a3 = a2 + kstepB; const char* b3 = b2 + kstepB;
;             if (last && has_next) S.a_ready(nxt);
;             if constexpr (SP2) {
;             PG8_LDB(B0, 0, 0); PG8_LDB(B1, 0, 1); PG8_SCHED; PG8_LDA(At, 0, 0); PG8_STAGE(PG8_SA(1, 1), a1 + hstepB, voffA);
;             PG8_WAIT_V(8); PG8_WAIT_L(0); PG8_BAR; PG8_MMA(0, 0, At, B0); PG8_MMA(0, 1, At, B1); PG8_BAR; PG8_SCHED;
;             PG8_LDA(At, 0, 1); PG8_STAGE(PG8_SB(0, 0), b2, voffB); PG8_STAGE(PG8_SB(0, 1), b2 + hstepB, voffB); PG8_STAGE(PG8_SA(0, 0), a2, voffA);
;             PG8_WAIT_V(8); PG8_WAIT_L(0); PG8_BAR; PG8_MMA(1, 0, At, B0); PG8_MMA(1, 1, At, B1); PG8_BAR; PG8_SCHED;
.LBB0_193:
	s_add_i32 s84, s38, 2
	s_add_u32 s39, s36, 0x4000
	s_addc_u32 s40, s37, 0
	s_cmp_eq_u32 s31, s38
	s_cselect_b32 s42, s8, s39
	s_cselect_b32 s43, s9, s40
	s_cselect_b32 s40, s62, s78
	s_cselect_b32 s41, s63, s82
	s_add_u32 s38, s42, 0x8000
	s_addc_u32 s39, s43, 0
	s_add_i32 s90, 0, 0x10000
	s_add_i32 s64, 0, 0x14000
	v_add_u32_e32 v140, s90, v174
	v_add_u32_e32 v161, s64, v174
	ds_read_b128 v[128:131], v140
	ds_read_b128 v[132:135], v140 offset:1024
	ds_read_b128 v[136:139], v140 offset:2048
	ds_read_b128 v[140:143], v140 offset:3072
	ds_read_b128 v[144:147], v161
	ds_read_b128 v[148:151], v161 offset:1024
	ds_read_b128 v[178:181], v161 offset:2048
	ds_read_b128 v[182:185], v161 offset:3072
	v_lshl_add_u64 v[172:173], s[36:37], 0, v[168:169]
	s_add_i32 m0, s21, 0xc000
	ds_read_b128 v[186:189], v177
	ds_read_b128 v[190:193], v177 offset:1024
	ds_read_b128 v[194:197], v177 offset:2048
	ds_read_b128 v[198:201], v177 offset:3072
	ds_read_b128 v[202:205], v177 offset:4096
	ds_read_b128 v[206:209], v177 offset:5120
	ds_read_b128 v[210:213], v177 offset:6144
	ds_read_b128 v[214:217], v177 offset:7168
	global_load_lds_dwordx4 v[172:173], off
	v_lshl_add_u64 v[172:173], s[36:37], 0, v[170:171]
	s_add_i32 m0, s21, 0xe000
	s_nop 0
	global_load_lds_dwordx4 v[172:173], off
	s_waitcnt vmcnt(8)
	s_waitcnt lgkmcnt(0)
	s_barrier
	s_setprio 1
	s_waitcnt lgkmcnt(0)
	v_mfma_f32_16x16x32_bf16 v[124:127], v[128:131], v[186:189], v[124:127]
	v_mfma_f32_16x16x32_bf16 v[124:127], v[132:135], v[190:193], v[124:127]
	v_mfma_f32_16x16x32_bf16 v[120:123], v[136:139], v[186:189], v[120:123]
	v_mfma_f32_16x16x32_bf16 v[120:123], v[140:143], v[190:193], v[120:123]
	v_mfma_f32_16x16x32_bf16 v[108:111], v[128:131], v[194:197], v[108:111]
	v_mfma_f32_16x16x32_bf16 v[108:111], v[132:135], v[198:201], v[108:111]
	v_mfma_f32_16x16x32_bf16 v[104:107], v[136:139], v[194:197], v[104:107]
	v_mfma_f32_16x16x32_bf16 v[104:107], v[140:143], v[198:201], v[104:107]
	v_mfma_f32_16x16x32_bf16 v[92:95], v[128:131], v[202:205], v[92:95]
	v_mfma_f32_16x16x32_bf16 v[92:95], v[132:135], v[206:209], v[92:95]
	v_mfma_f32_16x16x32_bf16 v[88:91], v[136:139], v[202:205], v[88:91]
	v_mfma_f32_16x16x32_bf16 v[88:91], v[140:143], v[206:209], v[88:91]
	v_mfma_f32_16x16x32_bf16 v[76:79], v[128:131], v[210:213], v[76:79]
	v_mfma_f32_16x16x32_bf16 v[76:79], v[132:135], v[214:217], v[76:79]
	v_mfma_f32_16x16x32_bf16 v[72:75], v[136:139], v[210:213], v[72:75]
	v_mfma_f32_16x16x32_bf16 v[72:75], v[140:143], v[214:217], v[72:75]
	v_mfma_f32_16x16x32_bf16 v[116:119], v[144:147], v[186:189], v[116:119]
	v_mfma_f32_16x16x32_bf16 v[116:119], v[148:151], v[190:193], v[116:119]
	v_mfma_f32_16x16x32_bf16 v[112:115], v[178:181], v[186:189], v[112:115]
	v_mfma_f32_16x16x32_bf16 v[112:115], v[182:185], v[190:193], v[112:115]
	v_mfma_f32_16x16x32_bf16 v[100:103], v[144:147], v[194:197], v[100:103]
	v_mfma_f32_16x16x32_bf16 v[100:103], v[148:151], v[198:201], v[100:103]
	v_mfma_f32_16x16x32_bf16 v[96:99], v[178:181], v[194:197], v[96:99]
	v_mfma_f32_16x16x32_bf16 v[96:99], v[182:185], v[198:201], v[96:99]
	v_mfma_f32_16x16x32_bf16 v[84:87], v[144:147], v[202:205], v[84:87]
	v_mfma_f32_16x16x32_bf16 v[84:87], v[148:151], v[206:209], v[84:87]
	v_mfma_f32_16x16x32_bf16 v[80:83], v[178:181], v[202:205], v[80:83]
	v_mfma_f32_16x16x32_bf16 v[80:83], v[182:185], v[206:209], v[80:83]
	v_mfma_f32_16x16x32_bf16 v[68:71], v[144:147], v[210:213], v[68:71]
	v_mfma_f32_16x16x32_bf16 v[68:71], v[148:151], v[214:217], v[68:71]
	v_mfma_f32_16x16x32_bf16 v[64:67], v[178:181], v[210:213], v[64:67]
	v_mfma_f32_16x16x32_bf16 v[64:67], v[182:185], v[214:217], v[64:67]
	s_setprio 0
	s_barrier
	s_add_i32 s65, s90, s20
	v_lshl_add_u64 v[172:173], s[40:41], 0, v[156:157]
	s_mov_b32 m0, s65
	ds_read_b128 v[186:189], v177 offset:16384
	ds_read_b128 v[190:193], v177 offset:17408
	ds_read_b128 v[194:197], v177 offset:18432
	ds_read_b128 v[198:201], v177 offset:19456
	ds_read_b128 v[202:205], v177 offset:20480
	ds_read_b128 v[206:209], v177 offset:21504
	ds_read_b128 v[210:213], v177 offset:22528
	ds_read_b128 v[214:217], v177 offset:23552
	global_load_lds_dwordx4 v[172:173], off
	s_add_i32 m0, s65, 0x2000
	s_add_u32 vcc_lo, s40, 0x4000
	v_lshl_add_u64 v[172:173], s[40:41], 0, v[152:153]
	s_addc_u32 vcc_hi, s41, 0
	s_add_i32 s64, s64, s20
	global_load_lds_dwordx4 v[172:173], off
	v_lshl_add_u64 v[172:173], vcc, 0, v[156:157]
	s_mov_b32 m0, s64
	s_nop 0
	global_load_lds_dwordx4 v[172:173], off
	v_lshl_add_u64 v[172:173], vcc, 0, v[152:153]
	s_add_i32 m0, s64, 0x2000
	s_nop 0
	global_load_lds_dwordx4 v[172:173], off
	v_lshl_add_u64 v[172:173], s[42:43], 0, v[158:159]
	s_mov_b32 m0, s21
	s_nop 0
	global_load_lds_dwordx4 v[172:173], off
	v_lshl_add_u64 v[172:173], s[42:43], 0, v[154:155]
	s_mov_b32 m0, s22
	s_nop 0
	global_load_lds_dwordx4 v[172:173], off
	s_waitcnt vmcnt(8)
	s_waitcnt lgkmcnt(0)
	s_barrier
; #define PG8_STAGE(bufoff, gbase, voff) do { _Pragma("unroll") for (int _i = 0; _i < 2; ++_i) \
;         __builtin_amdgcn_global_load_lds((const unsigned*)((const char*)(gbase) + (voff)[_i]), (PG8_LAS unsigned*)(lds + (bufoff) + ldsw + _i * 8192), 16, 0, 0); } while (0)
; #define PG8_LDA(dst, b, h) do { _Pragma("unroll") for (int m = 0; m < 4; ++m) _Pragma("unroll") for (int k = 0; k < 2; ++k) dst[m][k] = *(const PG8_LAS bf16x8*)(lds + PG8_SA(b, h) + aoff + m * 2048 + k * 1024); } while (0)
; #define PG8_LDB(dst, b, h) do { _Pragma("unroll") for (int n = 0; n < 2; ++n) _Pragma("unroll") for (int k = 0; k < 2; ++k) dst[n][k] = *(const PG8_LAS bf16x8*)(lds + PG8_SB(b, h) + boff + n * 2048 + k * 1024); } while (0)
; #define PG8_MMA(ai, bj, At, Bt) do { __builtin_amdgcn_s_setprio(1); _Pragma("unroll") for (int m = 0; m < 4; ++m) _Pragma("unroll") for (int n = 0; n < 2; ++n) _Pragma("unroll") for (int k = 0; k < 2; ++k) \
;         acc[ai][bj][m][n] = __builtin_amdgcn_mfma_f32_16x16x32_bf16(Bt[n][k], At[m][k], acc[ai][bj][m][n], 0, 0, 0); __builtin_amdgcn_s_setprio(0); } while (0)
; #define PG8_WAIT_V(n) asm volatile("s_waitcnt vmcnt(" #n ")" ::: "memory")
; #define PG8_WAIT_L(n) asm volatile("s_waitcnt lgkmcnt(" #n ")" ::: "memory")
; #define PG8_BAR __builtin_amdgcn_s_barrier()
; #define PG8_SCHED __builtin_amdgcn_sched_barrier(0)
; template <class Epi, class Sched, bool ALIGN_EPI = false, bool SP2 = false>
; __device__ __forceinline__ void gemm_phase(PG8_LAS unsigned char* lds, const Gemm g, const Sched& S, const Epi& E) {
;     ...
;             PG8_WAIT_V(8); PG8_WAIT_L(0); PG8_BAR; PG8_MMA(1, 0, At, B0); PG8_MMA(1, 1, At, B1); PG8_BAR; PG8_SCHED;
;             PG8_LDB(B0, 1, 0); PG8_LDB(B1, 1, 1); PG8_SCHED; PG8_LDA(At, 1, 0); PG8_STAGE(PG8_SA(0, 1), a2 + hstepB, voffA);
;             PG8_WAIT_V(8); PG8_WAIT_L(0); PG8_BAR; PG8_MMA(0, 0, At, B0); PG8_MMA(0, 1, At, B1); PG8_BAR; PG8_SCHED;
	s_setprio 1
	s_waitcnt lgkmcnt(0)
	v_mfma_f32_16x16x32_bf16 v[60:63], v[128:131], v[186:189], v[60:63]
	v_mfma_f32_16x16x32_bf16 v[60:63], v[132:135], v[190:193], v[60:63]
	v_mfma_f32_16x16x32_bf16 v[56:59], v[136:139], v[186:189], v[56:59]
	v_mfma_f32_16x16x32_bf16 v[56:59], v[140:143], v[190:193], v[56:59]
	v_mfma_f32_16x16x32_bf16 v[44:47], v[128:131], v[194:197], v[44:47]
	v_mfma_f32_16x16x32_bf16 v[44:47], v[132:135], v[198:201], v[44:47]
	v_mfma_f32_16x16x32_bf16 v[40:43], v[136:139], v[194:197], v[40:43]
	v_mfma_f32_16x16x32_bf16 v[40:43], v[140:143], v[198:201], v[40:43]
	v_mfma_f32_16x16x32_bf16 v[28:31], v[128:131], v[202:205], v[28:31]
	v_mfma_f32_16x16x32_bf16 v[28:31], v[132:135], v[206:209], v[28:31]
	v_mfma_f32_16x16x32_bf16 v[24:27], v[136:139], v[202:205], v[24:27]
	v_mfma_f32_16x16x32_bf16 v[24:27], v[140:143], v[206:209], v[24:27]
	v_mfma_f32_16x16x32_bf16 v[12:15], v[128:131], v[210:213], v[12:15]
	v_mfma_f32_16x16x32_bf16 v[12:15], v[132:135], v[214:217], v[12:15]
	v_mfma_f32_16x16x32_bf16 v[8:11], v[136:139], v[210:213], v[8:11]
	v_mfma_f32_16x16x32_bf16 v[8:11], v[140:143], v[214:217], v[8:11]
	v_mfma_f32_16x16x32_bf16 v[52:55], v[144:147], v[186:189], v[52:55]
	v_mfma_f32_16x16x32_bf16 v[52:55], v[148:151], v[190:193], v[52:55]
	v_mfma_f32_16x16x32_bf16 v[48:51], v[178:181], v[186:189], v[48:51]
	v_mfma_f32_16x16x32_bf16 v[48:51], v[182:185], v[190:193], v[48:51]
	v_mfma_f32_16x16x32_bf16 v[36:39], v[144:147], v[194:197], v[36:39]
	v_mfma_f32_16x16x32_bf16 v[36:39], v[148:151], v[198:201], v[36:39]
	v_mfma_f32_16x16x32_bf16 v[32:35], v[178:181], v[194:197], v[32:35]
	v_mfma_f32_16x16x32_bf16 v[32:35], v[182:185], v[198:201], v[32:35]
	v_mfma_f32_16x16x32_bf16 v[20:23], v[144:147], v[202:205], v[20:23]
	v_mfma_f32_16x16x32_bf16 v[20:23], v[148:151], v[206:209], v[20:23]
	v_mfma_f32_16x16x32_bf16 v[16:19], v[178:181], v[202:205], v[16:19]
	v_mfma_f32_16x16x32_bf16 v[16:19], v[182:185], v[206:209], v[16:19]
	v_mfma_f32_16x16x32_bf16 v[4:7], v[144:147], v[210:213], v[4:7]
	v_mfma_f32_16x16x32_bf16 v[4:7], v[148:151], v[214:217], v[4:7]
	v_mfma_f32_16x16x32_bf16 v[0:3], v[178:181], v[210:213], v[0:3]
	v_mfma_f32_16x16x32_bf16 v[0:3], v[182:185], v[214:217], v[0:3]
	s_setprio 0
	s_barrier
	s_add_i32 s64, 0, 0x18000
	s_add_i32 s65, 0, 0x1c000
	v_add_u32_e32 v140, s64, v174
	v_add_u32_e32 v161, s65, v174
	ds_read_b128 v[128:131], v140
	ds_read_b128 v[132:135], v140 offset:1024
	ds_read_b128 v[136:139], v140 offset:2048
	ds_read_b128 v[140:143], v140 offset:3072
	ds_read_b128 v[144:147], v161
	ds_read_b128 v[148:151], v161 offset:1024
	ds_read_b128 v[178:181], v161 offset:2048
	ds_read_b128 v[182:185], v161 offset:3072
	s_add_u32 s42, s42, 0x4000
	s_addc_u32 s43, s43, 0
	s_mov_b32 m0, s23
	v_lshl_add_u64 v[172:173], s[42:43], 0, v[158:159]
	ds_read_b128 v[186:189], v177 offset:32768
	ds_read_b128 v[190:193], v177 offset:33792
	ds_read_b128 v[194:197], v177 offset:34816
	ds_read_b128 v[198:201], v177 offset:35840
	ds_read_b128 v[202:205], v177 offset:36864
	ds_read_b128 v[206:209], v177 offset:37888
	ds_read_b128 v[210:213], v177 offset:38912
	ds_read_b128 v[214:217], v177 offset:39936
	global_load_lds_dwordx4 v[172:173], off
	v_lshl_add_u64 v[172:173], s[42:43], 0, v[154:155]
	s_mov_b32 m0, s24
	s_nop 0
	global_load_lds_dwordx4 v[172:173], off
	s_waitcnt vmcnt(8)
	s_waitcnt lgkmcnt(0)
	s_barrier
	s_setprio 1
	s_waitcnt lgkmcnt(0)
	v_mfma_f32_16x16x32_bf16 v[124:127], v[128:131], v[186:189], v[124:127]
	v_mfma_f32_16x16x32_bf16 v[124:127], v[132:135], v[190:193], v[124:127]
	v_mfma_f32_16x16x32_bf16 v[120:123], v[136:139], v[186:189], v[120:123]
	v_mfma_f32_16x16x32_bf16 v[120:123], v[140:143], v[190:193], v[120:123]
	v_mfma_f32_16x16x32_bf16 v[108:111], v[128:131], v[194:197], v[108:111]
	v_mfma_f32_16x16x32_bf16 v[108:111], v[132:135], v[198:201], v[108:111]
	v_mfma_f32_16x16x32_bf16 v[104:107], v[136:139], v[194:197], v[104:107]
	v_mfma_f32_16x16x32_bf16 v[104:107], v[140:143], v[198:201], v[104:107]
	v_mfma_f32_16x16x32_bf16 v[92:95], v[128:131], v[202:205], v[92:95]
	v_mfma_f32_16x16x32_bf16 v[92:95], v[132:135], v[206:209], v[92:95]
	v_mfma_f32_16x16x32_bf16 v[88:91], v[136:139], v[202:205], v[88:91]
	v_mfma_f32_16x16x32_bf16 v[88:91], v[140:143], v[206:209], v[88:91]
	v_mfma_f32_16x16x32_bf16 v[76:79], v[128:131], v[210:213], v[76:79]
	v_mfma_f32_16x16x32_bf16 v[76:79], v[132:135], v[214:217], v[76:79]
	v_mfma_f32_16x16x32_bf16 v[72:75], v[136:139], v[210:213], v[72:75]
	v_mfma_f32_16x16x32_bf16 v[72:75], v[140:143], v[214:217], v[72:75]
	v_mfma_f32_16x16x32_bf16 v[116:119], v[144:147], v[186:189], v[116:119]
	v_mfma_f32_16x16x32_bf16 v[116:119], v[148:151], v[190:193], v[116:119]
	v_mfma_f32_16x16x32_bf16 v[112:115], v[178:181], v[186:189], v[112:115]
	v_mfma_f32_16x16x32_bf16 v[112:115], v[182:185], v[190:193], v[112:115]
	v_mfma_f32_16x16x32_bf16 v[100:103], v[144:147], v[194:197], v[100:103]
	v_mfma_f32_16x16x32_bf16 v[100:103], v[148:151], v[198:201], v[100:103]
	v_mfma_f32_16x16x32_bf16 v[96:99], v[178:181], v[194:197], v[96:99]
	v_mfma_f32_16x16x32_bf16 v[96:99], v[182:185], v[198:201], v[96:99]
	v_mfma_f32_16x16x32_bf16 v[84:87], v[144:147], v[202:205], v[84:87]
	v_mfma_f32_16x16x32_bf16 v[84:87], v[148:151], v[206:209], v[84:87]
	v_mfma_f32_16x16x32_bf16 v[80:83], v[178:181], v[202:205], v[80:83]
	v_mfma_f32_16x16x32_bf16 v[80:83], v[182:185], v[206:209], v[80:83]
	v_mfma_f32_16x16x32_bf16 v[68:71], v[144:147], v[210:213], v[68:71]
	v_mfma_f32_16x16x32_bf16 v[68:71], v[148:151], v[214:217], v[68:71]
	v_mfma_f32_16x16x32_bf16 v[64:67], v[178:181], v[210:213], v[64:67]
	v_mfma_f32_16x16x32_bf16 v[64:67], v[182:185], v[214:217], v[64:67]
	s_setprio 0
	s_barrier
; #define PG8_STAGE(bufoff, gbase, voff) do { _Pragma("unroll") for (int _i = 0; _i < 2; ++_i) \
;         __builtin_amdgcn_global_load_lds((const unsigned*)((const char*)(gbase) + (voff)[_i]), (PG8_LAS unsigned*)(lds + (bufoff) + ldsw + _i * 8192), 16, 0, 0); } while (0)
; #define PG8_LDA(dst, b, h) do { _Pragma("unroll") for (int m = 0; m < 4; ++m) _Pragma("unroll") for (int k = 0; k < 2; ++k) dst[m][k] = *(const PG8_LAS bf16x8*)(lds + PG8_SA(b, h) + aoff + m * 2048 + k * 1024); } while (0)
; #define PG8_MMA(ai, bj, At, Bt) do { __builtin_amdgcn_s_setprio(1); _Pragma("unroll") for (int m = 0; m < 4; ++m) _Pragma("unroll") for (int n = 0; n < 2; ++n) _Pragma("unroll") for (int k = 0; k < 2; ++k) \
;         acc[ai][bj][m][n] = __builtin_amdgcn_mfma_f32_16x16x32_bf16(Bt[n][k], At[m][k], acc[ai][bj][m][n], 0, 0, 0); __builtin_amdgcn_s_setprio(0); } while (0)
; #define PG8_WAIT_V(n) asm volatile("s_waitcnt vmcnt(" #n ")" ::: "memory")
; #define PG8_WAIT_L(n) asm volatile("s_waitcnt lgkmcnt(" #n ")" ::: "memory")
; #define PG8_BAR __builtin_amdgcn_s_barrier()
; #define PG8_SCHED __builtin_amdgcn_sched_barrier(0)
; template <class Epi, class Sched, bool ALIGN_EPI = false, bool SP2 = false>
; __device__ __forceinline__ void gemm_phase(PG8_LAS unsigned char* lds, const Gemm g, const Sched& S, const Epi& E) {
;     ...
;         for (int t = 0; t < nt; t += 2) {
;             const bool last = (t == nt - 2);
;     ...
;             PG8_LDA(At, 1, 1); PG8_STAGE(PG8_SB(1, 0), b3, voffB); PG8_STAGE(PG8_SB(1, 1), b3 + hstepB, voffB); PG8_STAGE(PG8_SA(1, 0), a3, voffA);
;             PG8_WAIT_V(8); PG8_WAIT_L(0); PG8_BAR; PG8_MMA(1, 0, At, B0); PG8_MMA(1, 1, At, B1); PG8_BAR; PG8_SCHED;
	s_add_u32 s42, s40, 0x8000
	s_addc_u32 s43, s41, 0
	s_add_i32 s64, s64, s20
	v_lshl_add_u64 v[172:173], s[42:43], 0, v[156:157]
	s_mov_b32 m0, s64
	ds_read_b128 v[186:189], v177 offset:49152
	ds_read_b128 v[190:193], v177 offset:50176
	ds_read_b128 v[194:197], v177 offset:51200
	ds_read_b128 v[198:201], v177 offset:52224
	ds_read_b128 v[202:205], v177 offset:53248
	ds_read_b128 v[206:209], v177 offset:54272
	ds_read_b128 v[210:213], v177 offset:55296
	ds_read_b128 v[214:217], v177 offset:56320
	global_load_lds_dwordx4 v[172:173], off
	s_add_i32 m0, s64, 0x2000
	s_add_u32 s40, s40, 0xc000
	v_lshl_add_u64 v[172:173], s[42:43], 0, v[152:153]
	s_addc_u32 s41, s41, 0
	s_add_i32 s42, s65, s20
	global_load_lds_dwordx4 v[172:173], off
	v_lshl_add_u64 v[172:173], s[40:41], 0, v[156:157]
	s_mov_b32 m0, s42
	s_nop 0
	global_load_lds_dwordx4 v[172:173], off
	v_lshl_add_u64 v[172:173], s[40:41], 0, v[152:153]
	s_add_i32 m0, s42, 0x2000
	s_nop 0
	global_load_lds_dwordx4 v[172:173], off
	v_lshl_add_u64 v[172:173], s[38:39], 0, v[158:159]
	s_mov_b32 m0, s29
	s_nop 0
	global_load_lds_dwordx4 v[172:173], off
	v_lshl_add_u64 v[172:173], s[38:39], 0, v[154:155]
	s_mov_b32 m0, s30
	s_nop 0
	global_load_lds_dwordx4 v[172:173], off
	s_waitcnt vmcnt(8)
	s_waitcnt lgkmcnt(0)
	s_barrier
	s_setprio 1
	s_waitcnt lgkmcnt(0)
	v_mfma_f32_16x16x32_bf16 v[60:63], v[128:131], v[186:189], v[60:63]
	v_mfma_f32_16x16x32_bf16 v[60:63], v[132:135], v[190:193], v[60:63]
	v_mfma_f32_16x16x32_bf16 v[56:59], v[136:139], v[186:189], v[56:59]
	v_mfma_f32_16x16x32_bf16 v[56:59], v[140:143], v[190:193], v[56:59]
	v_mfma_f32_16x16x32_bf16 v[44:47], v[128:131], v[194:197], v[44:47]
	v_mfma_f32_16x16x32_bf16 v[44:47], v[132:135], v[198:201], v[44:47]
	v_mfma_f32_16x16x32_bf16 v[40:43], v[136:139], v[194:197], v[40:43]
	v_mfma_f32_16x16x32_bf16 v[40:43], v[140:143], v[198:201], v[40:43]
	v_mfma_f32_16x16x32_bf16 v[28:31], v[128:131], v[202:205], v[28:31]
	v_mfma_f32_16x16x32_bf16 v[28:31], v[132:135], v[206:209], v[28:31]
	v_mfma_f32_16x16x32_bf16 v[24:27], v[136:139], v[202:205], v[24:27]
	v_mfma_f32_16x16x32_bf16 v[24:27], v[140:143], v[206:209], v[24:27]
	v_mfma_f32_16x16x32_bf16 v[12:15], v[128:131], v[210:213], v[12:15]
	v_mfma_f32_16x16x32_bf16 v[12:15], v[132:135], v[214:217], v[12:15]
	v_mfma_f32_16x16x32_bf16 v[8:11], v[136:139], v[210:213], v[8:11]
	v_mfma_f32_16x16x32_bf16 v[8:11], v[140:143], v[214:217], v[8:11]
	v_mfma_f32_16x16x32_bf16 v[52:55], v[144:147], v[186:189], v[52:55]
	v_mfma_f32_16x16x32_bf16 v[52:55], v[148:151], v[190:193], v[52:55]
	v_mfma_f32_16x16x32_bf16 v[48:51], v[178:181], v[186:189], v[48:51]
	v_mfma_f32_16x16x32_bf16 v[48:51], v[182:185], v[190:193], v[48:51]
	v_mfma_f32_16x16x32_bf16 v[36:39], v[144:147], v[194:197], v[36:39]
	v_mfma_f32_16x16x32_bf16 v[36:39], v[148:151], v[198:201], v[36:39]
	v_mfma_f32_16x16x32_bf16 v[32:35], v[178:181], v[194:197], v[32:35]
	v_mfma_f32_16x16x32_bf16 v[32:35], v[182:185], v[198:201], v[32:35]
	v_mfma_f32_16x16x32_bf16 v[20:23], v[144:147], v[202:205], v[20:23]
	v_mfma_f32_16x16x32_bf16 v[20:23], v[148:151], v[206:209], v[20:23]
	v_mfma_f32_16x16x32_bf16 v[16:19], v[178:181], v[202:205], v[16:19]
	v_mfma_f32_16x16x32_bf16 v[16:19], v[182:185], v[206:209], v[16:19]
	v_mfma_f32_16x16x32_bf16 v[4:7], v[144:147], v[210:213], v[4:7]
	v_mfma_f32_16x16x32_bf16 v[4:7], v[148:151], v[214:217], v[4:7]
	v_mfma_f32_16x16x32_bf16 v[0:3], v[178:181], v[210:213], v[0:3]
	v_mfma_f32_16x16x32_bf16 v[0:3], v[182:185], v[214:217], v[0:3]
	s_setprio 0
	s_barrier
	s_add_u32 s36, s36, 0x10000
	s_addc_u32 s37, s37, 0
	s_add_u32 s78, s78, 0x10000
	s_addc_u32 s82, s82, 0
	s_cmp_ge_u32 s84, s26
	s_mov_b32 s38, s84
	s_cbranch_scc0 .LBB0_193
	s_and_b64 vcc, exec, s[60:61]
	s_cbranch_vccz .LBB0_196
	s_barrier

; #define PG8_STAGE(bufoff, gbase, voff) do { _Pragma("unroll") for (int _i = 0; _i < 2; ++_i) \
;         __builtin_amdgcn_global_load_lds((const unsigned*)((const char*)(gbase) + (voff)[_i]), (PG8_LAS unsigned*)(lds + (bufoff) + ldsw + _i * 8192), 16, 0, 0); } while (0)
; #define PG8_LDA(dst, b, h) do { _Pragma("unroll") for (int m = 0; m < 4; ++m) _Pragma("unroll") for (int k = 0; k < 2; ++k) dst[m][k] = *(const PG8_LAS bf16x8*)(lds + PG8_SA(b, h) + aoff + m * 2048 + k * 1024); } while (0)
; #define PG8_LDB(dst, b, h) do { _Pragma("unroll") for (int n = 0; n < 2; ++n) _Pragma("unroll") for (int k = 0; k < 2; ++k) dst[n][k] = *(const PG8_LAS bf16x8*)(lds + PG8_SB(b, h) + boff + n * 2048 + k * 1024); } while (0)
; #define PG8_MMA(ai, bj, At, Bt) do { __builtin_amdgcn_s_setprio(1); _Pragma("unroll") for (int m = 0; m < 4; ++m) _Pragma("unroll") for (int n = 0; n < 2; ++n) _Pragma("unroll") for (int k = 0; k < 2; ++k) \
;         acc[ai][bj][m][n] = __builtin_amdgcn_mfma_f32_16x16x32_bf16(Bt[n][k], At[m][k], acc[ai][bj][m][n], 0, 0, 0); __builtin_amdgcn_s_setprio(0); } while (0)
; #define PG8_WAIT_V(n) asm volatile("s_waitcnt vmcnt(" #n ")" ::: "memory")
; #define PG8_WAIT_L(n) asm volatile("s_waitcnt lgkmcnt(" #n ")" ::: "memory")
; template <class Epi, class Sched, bool ALIGN_EPI = false, bool SP2 = false>
; __device__ __forceinline__ void gemm_phase(PG8_LAS unsigned char* lds, const Gemm g, const Sched& S, const Epi& E) {
;     ...
;             const bool last = (t == nt - 2);
;             const char* a1 = cA + (size_t)(t + 1) * kstepB;
;             const char* a2 = last ? nA : cA + (size_t)(t + 2) * kstepB; const char* b2 = last ? nB : cB + (size_t)(t + 2) * kstepB;
;             const char* a3 = a2 + kstepB; const char* b3 = b2 + kstepB;
;             if (last && has_next) S.a_ready(nxt);
;             if constexpr (SP2) {
;             PG8_LDB(B0, 0, 0); PG8_LDB(B1, 0, 1); PG8_SCHED; PG8_LDA(At, 0, 0); PG8_STAGE(PG8_SA(1, 1), a1 + hstepB, voffA);
;             PG8_WAIT_V(8); PG8_WAIT_L(0); PG8_BAR; PG8_MMA(0, 0, At, B0); PG8_MMA(0, 1, At, B1); PG8_BAR; PG8_SCHED;
;             PG8_LDA(At, 0, 1); PG8_STAGE(PG8_SB(0, 0), b2, voffB); PG8_STAGE(PG8_SB(0, 1), b2 + hstepB, voffB); PG8_STAGE(PG8_SA(0, 0), a2, voffA);
;             PG8_WAIT_V(8); PG8_WAIT_L(0); PG8_BAR; PG8_MMA(1, 0, At, B0); PG8_MMA(1, 1, At, B1); PG8_BAR; PG8_SCHED;
.LBB0_232:
	s_add_u32 s31, s36, 0x4000
	s_addc_u32 s38, s37, 0
	s_cmp_eq_u32 s30, 28
	s_cselect_b32 s42, s26, s31
	s_cselect_b32 s43, s13, s38
	s_cselect_b32 s40, s27, s28
	s_cselect_b32 s41, s11, s29
	s_add_u32 s38, s42, 0x8000
	s_addc_u32 s39, s43, 0
	s_add_i32 s31, 0, 0x10000
	s_add_i32 s60, 0, 0x14000
	v_add_u32_e32 v152, s31, v169
	v_add_u32_e32 v175, s60, v169
	ds_read_b128 v[128:131], v152
	ds_read_b128 v[132:135], v152 offset:1024
	ds_read_b128 v[148:151], v152 offset:2048
	ds_read_b128 v[152:155], v152 offset:3072
	ds_read_b128 v[156:159], v175
	ds_read_b128 v[160:163], v175 offset:1024
	ds_read_b128 v[164:167], v175 offset:2048
	ds_read_b128 v[176:179], v175 offset:3072
	v_lshl_add_u64 v[212:213], s[36:37], 0, v[144:145]
	s_add_i32 m0, s17, 0xc000
	ds_read_b128 v[180:183], v174
	ds_read_b128 v[184:187], v174 offset:1024
	ds_read_b128 v[188:191], v174 offset:2048
	ds_read_b128 v[192:195], v174 offset:3072
	ds_read_b128 v[196:199], v174 offset:4096
	ds_read_b128 v[200:203], v174 offset:5120
	ds_read_b128 v[204:207], v174 offset:6144
	ds_read_b128 v[208:211], v174 offset:7168
	global_load_lds_dwordx4 v[212:213], off
	v_lshl_add_u64 v[212:213], s[36:37], 0, v[146:147]
	s_add_i32 m0, s17, 0xe000
	s_nop 0
	global_load_lds_dwordx4 v[212:213], off
	s_waitcnt vmcnt(8)
	s_waitcnt lgkmcnt(0)
	s_barrier
	s_setprio 1
	s_waitcnt lgkmcnt(0)
	v_mfma_f32_16x16x32_bf16 v[124:127], v[128:131], v[180:183], v[124:127]
	v_mfma_f32_16x16x32_bf16 v[124:127], v[132:135], v[184:187], v[124:127]
	v_mfma_f32_16x16x32_bf16 v[120:123], v[148:151], v[180:183], v[120:123]
	v_mfma_f32_16x16x32_bf16 v[120:123], v[152:155], v[184:187], v[120:123]
	v_mfma_f32_16x16x32_bf16 v[108:111], v[128:131], v[188:191], v[108:111]
	v_mfma_f32_16x16x32_bf16 v[108:111], v[132:135], v[192:195], v[108:111]
	v_mfma_f32_16x16x32_bf16 v[104:107], v[148:151], v[188:191], v[104:107]
	v_mfma_f32_16x16x32_bf16 v[104:107], v[152:155], v[192:195], v[104:107]
	v_mfma_f32_16x16x32_bf16 v[92:95], v[128:131], v[196:199], v[92:95]
	v_mfma_f32_16x16x32_bf16 v[92:95], v[132:135], v[200:203], v[92:95]
	v_mfma_f32_16x16x32_bf16 v[88:91], v[148:151], v[196:199], v[88:91]
	v_mfma_f32_16x16x32_bf16 v[88:91], v[152:155], v[200:203], v[88:91]
	v_mfma_f32_16x16x32_bf16 v[76:79], v[128:131], v[204:207], v[76:79]
	v_mfma_f32_16x16x32_bf16 v[76:79], v[132:135], v[208:211], v[76:79]
	v_mfma_f32_16x16x32_bf16 v[72:75], v[148:151], v[204:207], v[72:75]
	v_mfma_f32_16x16x32_bf16 v[72:75], v[152:155], v[208:211], v[72:75]
	v_mfma_f32_16x16x32_bf16 v[116:119], v[156:159], v[180:183], v[116:119]
	v_mfma_f32_16x16x32_bf16 v[116:119], v[160:163], v[184:187], v[116:119]
	v_mfma_f32_16x16x32_bf16 v[112:115], v[164:167], v[180:183], v[112:115]
	v_mfma_f32_16x16x32_bf16 v[112:115], v[176:179], v[184:187], v[112:115]
	v_mfma_f32_16x16x32_bf16 v[100:103], v[156:159], v[188:191], v[100:103]
	v_mfma_f32_16x16x32_bf16 v[100:103], v[160:163], v[192:195], v[100:103]
	v_mfma_f32_16x16x32_bf16 v[96:99], v[164:167], v[188:191], v[96:99]
	v_mfma_f32_16x16x32_bf16 v[96:99], v[176:179], v[192:195], v[96:99]
	v_mfma_f32_16x16x32_bf16 v[84:87], v[156:159], v[196:199], v[84:87]
	v_mfma_f32_16x16x32_bf16 v[84:87], v[160:163], v[200:203], v[84:87]
	v_mfma_f32_16x16x32_bf16 v[80:83], v[164:167], v[196:199], v[80:83]
	v_mfma_f32_16x16x32_bf16 v[80:83], v[176:179], v[200:203], v[80:83]
	v_mfma_f32_16x16x32_bf16 v[68:71], v[156:159], v[204:207], v[68:71]
	v_mfma_f32_16x16x32_bf16 v[68:71], v[160:163], v[208:211], v[68:71]
	v_mfma_f32_16x16x32_bf16 v[64:67], v[164:167], v[204:207], v[64:67]
	v_mfma_f32_16x16x32_bf16 v[64:67], v[176:179], v[208:211], v[64:67]
	s_setprio 0
	s_barrier
	s_add_i32 s31, s31, s14
	v_lshl_add_u64 v[212:213], s[40:41], 0, v[220:221]
	s_mov_b32 m0, s31
	ds_read_b128 v[180:183], v174 offset:16384
	ds_read_b128 v[184:187], v174 offset:17408
	ds_read_b128 v[188:191], v174 offset:18432
	ds_read_b128 v[192:195], v174 offset:19456
	ds_read_b128 v[196:199], v174 offset:20480
	ds_read_b128 v[200:203], v174 offset:21504
	ds_read_b128 v[204:207], v174 offset:22528
	ds_read_b128 v[208:211], v174 offset:23552
	global_load_lds_dwordx4 v[212:213], off
	s_add_i32 m0, s31, 0x2000
	s_add_u32 s44, s40, 0x4000
	v_lshl_add_u64 v[212:213], s[40:41], 0, v[136:137]
	s_addc_u32 s45, s41, 0
	s_add_i32 s31, s60, s14
	global_load_lds_dwordx4 v[212:213], off
	v_lshl_add_u64 v[212:213], s[44:45], 0, v[220:221]
	s_mov_b32 m0, s31
	s_nop 0
	global_load_lds_dwordx4 v[212:213], off
	v_lshl_add_u64 v[212:213], s[44:45], 0, v[136:137]
	s_add_i32 m0, s31, 0x2000
	s_nop 0
	global_load_lds_dwordx4 v[212:213], off
	v_lshl_add_u64 v[212:213], s[42:43], 0, v[140:141]
	s_mov_b32 m0, s17
	s_nop 0
	global_load_lds_dwordx4 v[212:213], off
	v_lshl_add_u64 v[212:213], s[42:43], 0, v[138:139]
	s_mov_b32 m0, s18
	s_nop 0
	global_load_lds_dwordx4 v[212:213], off
	s_waitcnt vmcnt(8)
	s_waitcnt lgkmcnt(0)
	s_barrier
; #define PG8_STAGE(bufoff, gbase, voff) do { _Pragma("unroll") for (int _i = 0; _i < 2; ++_i) \
;         __builtin_amdgcn_global_load_lds((const unsigned*)((const char*)(gbase) + (voff)[_i]), (PG8_LAS unsigned*)(lds + (bufoff) + ldsw + _i * 8192), 16, 0, 0); } while (0)
; #define PG8_LDA(dst, b, h) do { _Pragma("unroll") for (int m = 0; m < 4; ++m) _Pragma("unroll") for (int k = 0; k < 2; ++k) dst[m][k] = *(const PG8_LAS bf16x8*)(lds + PG8_SA(b, h) + aoff + m * 2048 + k * 1024); } while (0)
; #define PG8_LDB(dst, b, h) do { _Pragma("unroll") for (int n = 0; n < 2; ++n) _Pragma("unroll") for (int k = 0; k < 2; ++k) dst[n][k] = *(const PG8_LAS bf16x8*)(lds + PG8_SB(b, h) + boff + n * 2048 + k * 1024); } while (0)
; #define PG8_MMA(ai, bj, At, Bt) do { __builtin_amdgcn_s_setprio(1); _Pragma("unroll") for (int m = 0; m < 4; ++m) _Pragma("unroll") for (int n = 0; n < 2; ++n) _Pragma("unroll") for (int k = 0; k < 2; ++k) \
;         acc[ai][bj][m][n] = __builtin_amdgcn_mfma_f32_16x16x32_bf16(Bt[n][k], At[m][k], acc[ai][bj][m][n], 0, 0, 0); __builtin_amdgcn_s_setprio(0); } while (0)
; #define PG8_WAIT_V(n) asm volatile("s_waitcnt vmcnt(" #n ")" ::: "memory")
; #define PG8_WAIT_L(n) asm volatile("s_waitcnt lgkmcnt(" #n ")" ::: "memory")
; #define PG8_BAR __builtin_amdgcn_s_barrier()
; #define PG8_SCHED __builtin_amdgcn_sched_barrier(0)
; template <class Epi, class Sched, bool ALIGN_EPI = false, bool SP2 = false>
; __device__ __forceinline__ void gemm_phase(PG8_LAS unsigned char* lds, const Gemm g, const Sched& S, const Epi& E) {
;     ...
;             PG8_WAIT_V(8); PG8_WAIT_L(0); PG8_BAR; PG8_MMA(1, 0, At, B0); PG8_MMA(1, 1, At, B1); PG8_BAR; PG8_SCHED;
;             PG8_LDB(B0, 1, 0); PG8_LDB(B1, 1, 1); PG8_SCHED; PG8_LDA(At, 1, 0); PG8_STAGE(PG8_SA(0, 1), a2 + hstepB, voffA);
;             PG8_WAIT_V(8); PG8_WAIT_L(0); PG8_BAR; PG8_MMA(0, 0, At, B0); PG8_MMA(0, 1, At, B1); PG8_BAR; PG8_SCHED;
	s_setprio 1
	s_waitcnt lgkmcnt(0)
	v_mfma_f32_16x16x32_bf16 v[60:63], v[128:131], v[180:183], v[60:63]
	v_mfma_f32_16x16x32_bf16 v[60:63], v[132:135], v[184:187], v[60:63]
	v_mfma_f32_16x16x32_bf16 v[56:59], v[148:151], v[180:183], v[56:59]
	v_mfma_f32_16x16x32_bf16 v[56:59], v[152:155], v[184:187], v[56:59]
	v_mfma_f32_16x16x32_bf16 v[48:51], v[128:131], v[188:191], v[48:51]
	v_mfma_f32_16x16x32_bf16 v[48:51], v[132:135], v[192:195], v[48:51]
	v_mfma_f32_16x16x32_bf16 v[40:43], v[148:151], v[188:191], v[40:43]
	v_mfma_f32_16x16x32_bf16 v[40:43], v[152:155], v[192:195], v[40:43]
	v_mfma_f32_16x16x32_bf16 v[32:35], v[128:131], v[196:199], v[32:35]
	v_mfma_f32_16x16x32_bf16 v[32:35], v[132:135], v[200:203], v[32:35]
	v_mfma_f32_16x16x32_bf16 v[24:27], v[148:151], v[196:199], v[24:27]
	v_mfma_f32_16x16x32_bf16 v[24:27], v[152:155], v[200:203], v[24:27]
	v_mfma_f32_16x16x32_bf16 v[16:19], v[128:131], v[204:207], v[16:19]
	v_mfma_f32_16x16x32_bf16 v[16:19], v[132:135], v[208:211], v[16:19]
	v_mfma_f32_16x16x32_bf16 v[8:11], v[148:151], v[204:207], v[8:11]
	v_mfma_f32_16x16x32_bf16 v[8:11], v[152:155], v[208:211], v[8:11]
	v_mfma_f32_16x16x32_bf16 v[52:55], v[156:159], v[180:183], v[52:55]
	v_mfma_f32_16x16x32_bf16 v[52:55], v[160:163], v[184:187], v[52:55]
	v_mfma_f32_16x16x32_bf16 v[44:47], v[164:167], v[180:183], v[44:47]
	v_mfma_f32_16x16x32_bf16 v[44:47], v[176:179], v[184:187], v[44:47]
	v_mfma_f32_16x16x32_bf16 v[36:39], v[156:159], v[188:191], v[36:39]
	v_mfma_f32_16x16x32_bf16 v[36:39], v[160:163], v[192:195], v[36:39]
	v_mfma_f32_16x16x32_bf16 v[28:31], v[164:167], v[188:191], v[28:31]
	v_mfma_f32_16x16x32_bf16 v[28:31], v[176:179], v[192:195], v[28:31]
	v_mfma_f32_16x16x32_bf16 v[20:23], v[156:159], v[196:199], v[20:23]
	v_mfma_f32_16x16x32_bf16 v[20:23], v[160:163], v[200:203], v[20:23]
	v_mfma_f32_16x16x32_bf16 v[12:15], v[164:167], v[196:199], v[12:15]
	v_mfma_f32_16x16x32_bf16 v[12:15], v[176:179], v[200:203], v[12:15]
	v_mfma_f32_16x16x32_bf16 v[4:7], v[156:159], v[204:207], v[4:7]
	v_mfma_f32_16x16x32_bf16 v[4:7], v[160:163], v[208:211], v[4:7]
	v_mfma_f32_16x16x32_bf16 v[0:3], v[164:167], v[204:207], v[0:3]
	v_mfma_f32_16x16x32_bf16 v[0:3], v[176:179], v[208:211], v[0:3]
	s_setprio 0
	s_barrier
	s_add_i32 s31, 0, 0x18000
	s_add_i32 s44, 0, 0x1c000
	v_add_u32_e32 v152, s31, v169
	v_add_u32_e32 v175, s44, v169
	ds_read_b128 v[128:131], v152
	ds_read_b128 v[132:135], v152 offset:1024
	ds_read_b128 v[148:151], v152 offset:2048
	ds_read_b128 v[152:155], v152 offset:3072
	ds_read_b128 v[156:159], v175
	ds_read_b128 v[160:163], v175 offset:1024
	ds_read_b128 v[164:167], v175 offset:2048
	ds_read_b128 v[176:179], v175 offset:3072
	s_add_u32 s42, s42, 0x4000
	s_addc_u32 s43, s43, 0
	s_mov_b32 m0, s19
	v_lshl_add_u64 v[212:213], s[42:43], 0, v[140:141]
	ds_read_b128 v[180:183], v174 offset:32768
	ds_read_b128 v[184:187], v174 offset:33792
	ds_read_b128 v[188:191], v174 offset:34816
	ds_read_b128 v[192:195], v174 offset:35840
	ds_read_b128 v[196:199], v174 offset:36864
	ds_read_b128 v[200:203], v174 offset:37888
	ds_read_b128 v[204:207], v174 offset:38912
	ds_read_b128 v[208:211], v174 offset:39936
	global_load_lds_dwordx4 v[212:213], off
	v_lshl_add_u64 v[212:213], s[42:43], 0, v[138:139]
	s_mov_b32 m0, s20
	s_nop 0
	global_load_lds_dwordx4 v[212:213], off
	s_waitcnt vmcnt(8)
	s_waitcnt lgkmcnt(0)
	s_barrier
	s_setprio 1
	s_waitcnt lgkmcnt(0)
	v_mfma_f32_16x16x32_bf16 v[124:127], v[128:131], v[180:183], v[124:127]
	v_mfma_f32_16x16x32_bf16 v[124:127], v[132:135], v[184:187], v[124:127]
	v_mfma_f32_16x16x32_bf16 v[120:123], v[148:151], v[180:183], v[120:123]
	v_mfma_f32_16x16x32_bf16 v[120:123], v[152:155], v[184:187], v[120:123]
	v_mfma_f32_16x16x32_bf16 v[108:111], v[128:131], v[188:191], v[108:111]
	v_mfma_f32_16x16x32_bf16 v[108:111], v[132:135], v[192:195], v[108:111]
	v_mfma_f32_16x16x32_bf16 v[104:107], v[148:151], v[188:191], v[104:107]
	v_mfma_f32_16x16x32_bf16 v[104:107], v[152:155], v[192:195], v[104:107]
	v_mfma_f32_16x16x32_bf16 v[92:95], v[128:131], v[196:199], v[92:95]
	v_mfma_f32_16x16x32_bf16 v[92:95], v[132:135], v[200:203], v[92:95]
	v_mfma_f32_16x16x32_bf16 v[88:91], v[148:151], v[196:199], v[88:91]
	v_mfma_f32_16x16x32_bf16 v[88:91], v[152:155], v[200:203], v[88:91]
	v_mfma_f32_16x16x32_bf16 v[76:79], v[128:131], v[204:207], v[76:79]
	v_mfma_f32_16x16x32_bf16 v[76:79], v[132:135], v[208:211], v[76:79]
	v_mfma_f32_16x16x32_bf16 v[72:75], v[148:151], v[204:207], v[72:75]
	v_mfma_f32_16x16x32_bf16 v[72:75], v[152:155], v[208:211], v[72:75]
	v_mfma_f32_16x16x32_bf16 v[116:119], v[156:159], v[180:183], v[116:119]
	v_mfma_f32_16x16x32_bf16 v[116:119], v[160:163], v[184:187], v[116:119]
	v_mfma_f32_16x16x32_bf16 v[112:115], v[164:167], v[180:183], v[112:115]
	v_mfma_f32_16x16x32_bf16 v[112:115], v[176:179], v[184:187], v[112:115]
	v_mfma_f32_16x16x32_bf16 v[100:103], v[156:159], v[188:191], v[100:103]
	v_mfma_f32_16x16x32_bf16 v[100:103], v[160:163], v[192:195], v[100:103]
	v_mfma_f32_16x16x32_bf16 v[96:99], v[164:167], v[188:191], v[96:99]
	v_mfma_f32_16x16x32_bf16 v[96:99], v[176:179], v[192:195], v[96:99]
	v_mfma_f32_16x16x32_bf16 v[84:87], v[156:159], v[196:199], v[84:87]
	v_mfma_f32_16x16x32_bf16 v[84:87], v[160:163], v[200:203], v[84:87]
	v_mfma_f32_16x16x32_bf16 v[80:83], v[164:167], v[196:199], v[80:83]
	v_mfma_f32_16x16x32_bf16 v[80:83], v[176:179], v[200:203], v[80:83]
	v_mfma_f32_16x16x32_bf16 v[68:71], v[156:159], v[204:207], v[68:71]
	v_mfma_f32_16x16x32_bf16 v[68:71], v[160:163], v[208:211], v[68:71]
	v_mfma_f32_16x16x32_bf16 v[64:67], v[164:167], v[204:207], v[64:67]
	v_mfma_f32_16x16x32_bf16 v[64:67], v[176:179], v[208:211], v[64:67]
	s_setprio 0
	s_barrier
; #define PG8_STAGE(bufoff, gbase, voff) do { _Pragma("unroll") for (int _i = 0; _i < 2; ++_i) \
;         __builtin_amdgcn_global_load_lds((const unsigned*)((const char*)(gbase) + (voff)[_i]), (PG8_LAS unsigned*)(lds + (bufoff) + ldsw + _i * 8192), 16, 0, 0); } while (0)
; #define PG8_LDA(dst, b, h) do { _Pragma("unroll") for (int m = 0; m < 4; ++m) _Pragma("unroll") for (int k = 0; k < 2; ++k) dst[m][k] = *(const PG8_LAS bf16x8*)(lds + PG8_SA(b, h) + aoff + m * 2048 + k * 1024); } while (0)
; #define PG8_MMA(ai, bj, At, Bt) do { __builtin_amdgcn_s_setprio(1); _Pragma("unroll") for (int m = 0; m < 4; ++m) _Pragma("unroll") for (int n = 0; n < 2; ++n) _Pragma("unroll") for (int k = 0; k < 2; ++k) \
;         acc[ai][bj][m][n] = __builtin_amdgcn_mfma_f32_16x16x32_bf16(Bt[n][k], At[m][k], acc[ai][bj][m][n], 0, 0, 0); __builtin_amdgcn_s_setprio(0); } while (0)
; #define PG8_WAIT_V(n) asm volatile("s_waitcnt vmcnt(" #n ")" ::: "memory")
; #define PG8_WAIT_L(n) asm volatile("s_waitcnt lgkmcnt(" #n ")" ::: "memory")
; #define PG8_BAR __builtin_amdgcn_s_barrier()
; #define PG8_SCHED __builtin_amdgcn_sched_barrier(0)
; template <class Epi, class Sched, bool ALIGN_EPI = false, bool SP2 = false>
; __device__ __forceinline__ void gemm_phase(PG8_LAS unsigned char* lds, const Gemm g, const Sched& S, const Epi& E) {
;     ...
;         for (int t = 0; t < nt; t += 2) {
;             const bool last = (t == nt - 2);
;     ...
;             PG8_LDA(At, 1, 1); PG8_STAGE(PG8_SB(1, 0), b3, voffB); PG8_STAGE(PG8_SB(1, 1), b3 + hstepB, voffB); PG8_STAGE(PG8_SA(1, 0), a3, voffA);
;             PG8_WAIT_V(8); PG8_WAIT_L(0); PG8_BAR; PG8_MMA(1, 0, At, B0); PG8_MMA(1, 1, At, B1); PG8_BAR; PG8_SCHED;
	s_add_u32 s42, s40, 0x8000
	s_addc_u32 s43, s41, 0
	s_add_i32 s31, s31, s14
	v_lshl_add_u64 v[212:213], s[42:43], 0, v[220:221]
	s_mov_b32 m0, s31
	ds_read_b128 v[180:183], v174 offset:49152
	ds_read_b128 v[184:187], v174 offset:50176
	ds_read_b128 v[188:191], v174 offset:51200
	ds_read_b128 v[192:195], v174 offset:52224
	ds_read_b128 v[196:199], v174 offset:53248
	ds_read_b128 v[200:203], v174 offset:54272
	ds_read_b128 v[204:207], v174 offset:55296
	ds_read_b128 v[208:211], v174 offset:56320
	global_load_lds_dwordx4 v[212:213], off
	s_add_i32 m0, s31, 0x2000
	s_add_u32 s40, s40, 0xc000
	v_lshl_add_u64 v[212:213], s[42:43], 0, v[136:137]
	s_addc_u32 s41, s41, 0
	s_add_i32 s31, s44, s14
	global_load_lds_dwordx4 v[212:213], off
	v_lshl_add_u64 v[212:213], s[40:41], 0, v[220:221]
	s_mov_b32 m0, s31
	s_nop 0
	global_load_lds_dwordx4 v[212:213], off
	v_lshl_add_u64 v[212:213], s[40:41], 0, v[136:137]
	s_add_i32 m0, s31, 0x2000
	s_nop 0
	global_load_lds_dwordx4 v[212:213], off
	v_lshl_add_u64 v[212:213], s[38:39], 0, v[140:141]
	s_mov_b32 m0, s21
	s_nop 0
	global_load_lds_dwordx4 v[212:213], off
	v_lshl_add_u64 v[212:213], s[38:39], 0, v[138:139]
	s_mov_b32 m0, s22
	s_nop 0
	global_load_lds_dwordx4 v[212:213], off
	s_waitcnt vmcnt(8)
	s_waitcnt lgkmcnt(0)
	s_barrier
	s_setprio 1
	s_waitcnt lgkmcnt(0)
	v_mfma_f32_16x16x32_bf16 v[60:63], v[128:131], v[180:183], v[60:63]
	v_mfma_f32_16x16x32_bf16 v[60:63], v[132:135], v[184:187], v[60:63]
	v_mfma_f32_16x16x32_bf16 v[56:59], v[148:151], v[180:183], v[56:59]
	v_mfma_f32_16x16x32_bf16 v[56:59], v[152:155], v[184:187], v[56:59]
	v_mfma_f32_16x16x32_bf16 v[48:51], v[128:131], v[188:191], v[48:51]
	v_mfma_f32_16x16x32_bf16 v[48:51], v[132:135], v[192:195], v[48:51]
	v_mfma_f32_16x16x32_bf16 v[40:43], v[148:151], v[188:191], v[40:43]
	v_mfma_f32_16x16x32_bf16 v[40:43], v[152:155], v[192:195], v[40:43]
	v_mfma_f32_16x16x32_bf16 v[32:35], v[128:131], v[196:199], v[32:35]
	v_mfma_f32_16x16x32_bf16 v[32:35], v[132:135], v[200:203], v[32:35]
	v_mfma_f32_16x16x32_bf16 v[24:27], v[148:151], v[196:199], v[24:27]
	v_mfma_f32_16x16x32_bf16 v[24:27], v[152:155], v[200:203], v[24:27]
	v_mfma_f32_16x16x32_bf16 v[16:19], v[128:131], v[204:207], v[16:19]
	v_mfma_f32_16x16x32_bf16 v[16:19], v[132:135], v[208:211], v[16:19]
	v_mfma_f32_16x16x32_bf16 v[8:11], v[148:151], v[204:207], v[8:11]
	v_mfma_f32_16x16x32_bf16 v[8:11], v[152:155], v[208:211], v[8:11]
	v_mfma_f32_16x16x32_bf16 v[52:55], v[156:159], v[180:183], v[52:55]
	v_mfma_f32_16x16x32_bf16 v[52:55], v[160:163], v[184:187], v[52:55]
	v_mfma_f32_16x16x32_bf16 v[44:47], v[164:167], v[180:183], v[44:47]
	v_mfma_f32_16x16x32_bf16 v[44:47], v[176:179], v[184:187], v[44:47]
	v_mfma_f32_16x16x32_bf16 v[36:39], v[156:159], v[188:191], v[36:39]
	v_mfma_f32_16x16x32_bf16 v[36:39], v[160:163], v[192:195], v[36:39]
	v_mfma_f32_16x16x32_bf16 v[28:31], v[164:167], v[188:191], v[28:31]
	v_mfma_f32_16x16x32_bf16 v[28:31], v[176:179], v[192:195], v[28:31]
	v_mfma_f32_16x16x32_bf16 v[20:23], v[156:159], v[196:199], v[20:23]
	v_mfma_f32_16x16x32_bf16 v[20:23], v[160:163], v[200:203], v[20:23]
	v_mfma_f32_16x16x32_bf16 v[12:15], v[164:167], v[196:199], v[12:15]
	v_mfma_f32_16x16x32_bf16 v[12:15], v[176:179], v[200:203], v[12:15]
	v_mfma_f32_16x16x32_bf16 v[4:7], v[156:159], v[204:207], v[4:7]
	v_mfma_f32_16x16x32_bf16 v[4:7], v[160:163], v[208:211], v[4:7]
	v_mfma_f32_16x16x32_bf16 v[0:3], v[164:167], v[204:207], v[0:3]
	v_mfma_f32_16x16x32_bf16 v[0:3], v[176:179], v[208:211], v[0:3]
	s_setprio 0
	s_barrier
	s_add_i32 s30, s30, 2
	s_add_u32 s36, s36, 0x10000
	s_addc_u32 s37, s37, 0
	s_add_u32 s28, s28, 0x10000
	s_addc_u32 s29, s29, 0
	s_cmp_gt_u32 s30, 29
	s_cbranch_scc0 .LBB0_232
	s_and_b64 vcc, exec, s[8:9]
	s_cbranch_vccz .LBB0_235
	s_barrier

; #define PG8_STAGE(bufoff, gbase, voff) do { _Pragma("unroll") for (int _i = 0; _i < 2; ++_i) \
;         __builtin_amdgcn_global_load_lds((const unsigned*)((const char*)(gbase) + (voff)[_i]), (PG8_LAS unsigned*)(lds + (bufoff) + ldsw + _i * 8192), 16, 0, 0); } while (0)
; #define PG8_LDA(dst, b, h) do { _Pragma("unroll") for (int m = 0; m < 4; ++m) _Pragma("unroll") for (int k = 0; k < 2; ++k) dst[m][k] = *(const PG8_LAS bf16x8*)(lds + PG8_SA(b, h) + aoff + m * 2048 + k * 1024); } while (0)
; #define PG8_LDB(dst, b, h) do { _Pragma("unroll") for (int n = 0; n < 2; ++n) _Pragma("unroll") for (int k = 0; k < 2; ++k) dst[n][k] = *(const PG8_LAS bf16x8*)(lds + PG8_SB(b, h) + boff + n * 2048 + k * 1024); } while (0)
; #define PG8_MMA(ai, bj, At, Bt) do { __builtin_amdgcn_s_setprio(1); _Pragma("unroll") for (int m = 0; m < 4; ++m) _Pragma("unroll") for (int n = 0; n < 2; ++n) _Pragma("unroll") for (int k = 0; k < 2; ++k) \
;         acc[ai][bj][m][n] = __builtin_amdgcn_mfma_f32_16x16x32_bf16(Bt[n][k], At[m][k], acc[ai][bj][m][n], 0, 0, 0); __builtin_amdgcn_s_setprio(0); } while (0)
; #define PG8_WAIT_V(n) asm volatile("s_waitcnt vmcnt(" #n ")" ::: "memory")
; #define PG8_WAIT_L(n) asm volatile("s_waitcnt lgkmcnt(" #n ")" ::: "memory")
; template <class Epi, class Sched, bool ALIGN_EPI = false, bool SP2 = false>
; __device__ __forceinline__ void gemm_phase(PG8_LAS unsigned char* lds, const Gemm g, const Sched& S, const Epi& E) {
;     ...
;             const bool last = (t == nt - 2);
;             const char* a1 = cA + (size_t)(t + 1) * kstepB;
;             const char* a2 = last ? nA : cA + (size_t)(t + 2) * kstepB; const char* b2 = last ? nB : cB + (size_t)(t + 2) * kstepB;
;             const char* a3 = a2 + kstepB; const char* b3 = b2 + kstepB;
;             if (last && has_next) S.a_ready(nxt);
;             if constexpr (SP2) {
;             PG8_LDB(B0, 0, 0); PG8_LDB(B1, 0, 1); PG8_SCHED; PG8_LDA(At, 0, 0); PG8_STAGE(PG8_SA(1, 1), a1 + hstepB, voffA);
;             PG8_WAIT_V(8); PG8_WAIT_L(0); PG8_BAR; PG8_MMA(0, 0, At, B0); PG8_MMA(0, 1, At, B1); PG8_BAR; PG8_SCHED;
;             PG8_LDA(At, 0, 1); PG8_STAGE(PG8_SB(0, 0), b2, voffB); PG8_STAGE(PG8_SB(0, 1), b2 + hstepB, voffB); PG8_STAGE(PG8_SA(0, 0), a2, voffA);
;             PG8_WAIT_V(8); PG8_WAIT_L(0); PG8_BAR; PG8_MMA(1, 0, At, B0); PG8_MMA(1, 1, At, B1); PG8_BAR; PG8_SCHED;
.LBB0_263:
	s_add_u32 s38, s36, 0x4000
	s_addc_u32 s39, s37, 0
	s_cmp_eq_u32 s62, 28
	s_cselect_b32 s42, s30, s38
	s_cselect_b32 s43, s13, s39
	s_cselect_b32 s40, s31, s44
	s_cselect_b32 s41, s11, s45
	s_add_u32 s38, s42, 0x8000
	s_addc_u32 s39, s43, 0
	s_add_i32 s63, 0, 0x10000
	v_add_u32_e32 v151, s63, v165
	s_add_i32 s75, 0, 0x14000
	ds_read_b128 v[128:131], v151
	ds_read_b128 v[132:135], v151 offset:1024
	ds_read_b128 v[152:155], v151 offset:2048
	ds_read_b128 v[156:159], v151 offset:3072
	v_add_u32_e32 v151, s75, v165
	ds_read_b128 v[160:163], v151
	ds_read_b128 v[170:173], v151 offset:1024
	ds_read_b128 v[174:177], v151 offset:2048
	ds_read_b128 v[178:181], v151 offset:3072
	v_lshl_add_u64 v[214:215], s[36:37], 0, v[146:147]
	s_add_i32 m0, s19, 0xc000
	ds_read_b128 v[182:185], v168
	ds_read_b128 v[186:189], v168 offset:1024
	ds_read_b128 v[190:193], v168 offset:2048
	ds_read_b128 v[194:197], v168 offset:3072
	ds_read_b128 v[198:201], v168 offset:4096
	ds_read_b128 v[202:205], v168 offset:5120
	ds_read_b128 v[206:209], v168 offset:6144
	ds_read_b128 v[210:213], v168 offset:7168
	global_load_lds_dwordx4 v[214:215], off
	v_lshl_add_u64 v[214:215], s[36:37], 0, v[148:149]
	s_add_i32 m0, s19, 0xe000
	s_nop 0
	global_load_lds_dwordx4 v[214:215], off
	s_waitcnt vmcnt(8)
	s_waitcnt lgkmcnt(0)
	s_barrier
	s_setprio 1
	s_waitcnt lgkmcnt(0)
	v_mfma_f32_16x16x32_bf16 v[124:127], v[128:131], v[182:185], v[124:127]
	v_mfma_f32_16x16x32_bf16 v[124:127], v[132:135], v[186:189], v[124:127]
	v_mfma_f32_16x16x32_bf16 v[116:119], v[152:155], v[182:185], v[116:119]
	v_mfma_f32_16x16x32_bf16 v[116:119], v[156:159], v[186:189], v[116:119]
	v_mfma_f32_16x16x32_bf16 v[108:111], v[128:131], v[190:193], v[108:111]
	v_mfma_f32_16x16x32_bf16 v[108:111], v[132:135], v[194:197], v[108:111]
	v_mfma_f32_16x16x32_bf16 v[100:103], v[152:155], v[190:193], v[100:103]
	v_mfma_f32_16x16x32_bf16 v[100:103], v[156:159], v[194:197], v[100:103]
	v_mfma_f32_16x16x32_bf16 v[92:95], v[128:131], v[198:201], v[92:95]
	v_mfma_f32_16x16x32_bf16 v[92:95], v[132:135], v[202:205], v[92:95]
	v_mfma_f32_16x16x32_bf16 v[84:87], v[152:155], v[198:201], v[84:87]
	v_mfma_f32_16x16x32_bf16 v[84:87], v[156:159], v[202:205], v[84:87]
	v_mfma_f32_16x16x32_bf16 v[76:79], v[128:131], v[206:209], v[76:79]
	v_mfma_f32_16x16x32_bf16 v[76:79], v[132:135], v[210:213], v[76:79]
	v_mfma_f32_16x16x32_bf16 v[68:71], v[152:155], v[206:209], v[68:71]
	v_mfma_f32_16x16x32_bf16 v[68:71], v[156:159], v[210:213], v[68:71]
	v_mfma_f32_16x16x32_bf16 v[120:123], v[160:163], v[182:185], v[120:123]
	v_mfma_f32_16x16x32_bf16 v[120:123], v[170:173], v[186:189], v[120:123]
	v_mfma_f32_16x16x32_bf16 v[112:115], v[174:177], v[182:185], v[112:115]
	v_mfma_f32_16x16x32_bf16 v[112:115], v[178:181], v[186:189], v[112:115]
	v_mfma_f32_16x16x32_bf16 v[104:107], v[160:163], v[190:193], v[104:107]
	v_mfma_f32_16x16x32_bf16 v[104:107], v[170:173], v[194:197], v[104:107]
	v_mfma_f32_16x16x32_bf16 v[96:99], v[174:177], v[190:193], v[96:99]
	v_mfma_f32_16x16x32_bf16 v[96:99], v[178:181], v[194:197], v[96:99]
	v_mfma_f32_16x16x32_bf16 v[88:91], v[160:163], v[198:201], v[88:91]
	v_mfma_f32_16x16x32_bf16 v[88:91], v[170:173], v[202:205], v[88:91]
	v_mfma_f32_16x16x32_bf16 v[80:83], v[174:177], v[198:201], v[80:83]
	v_mfma_f32_16x16x32_bf16 v[80:83], v[178:181], v[202:205], v[80:83]
	v_mfma_f32_16x16x32_bf16 v[72:75], v[160:163], v[206:209], v[72:75]
	v_mfma_f32_16x16x32_bf16 v[72:75], v[170:173], v[210:213], v[72:75]
	v_mfma_f32_16x16x32_bf16 v[64:67], v[174:177], v[206:209], v[64:67]
	v_mfma_f32_16x16x32_bf16 v[64:67], v[178:181], v[210:213], v[64:67]
	s_setprio 0
	s_barrier
	s_add_i32 s63, s63, s16
	v_lshl_add_u64 v[214:215], s[40:41], 0, v[140:141]
	s_mov_b32 m0, s63
	ds_read_b128 v[182:185], v168 offset:16384
	ds_read_b128 v[186:189], v168 offset:17408
	ds_read_b128 v[190:193], v168 offset:18432
	ds_read_b128 v[194:197], v168 offset:19456
	ds_read_b128 v[198:201], v168 offset:20480
	ds_read_b128 v[202:205], v168 offset:21504
	ds_read_b128 v[206:209], v168 offset:22528
	ds_read_b128 v[210:213], v168 offset:23552
	global_load_lds_dwordx4 v[214:215], off
	s_add_i32 m0, s63, 0x2000
	s_add_u32 s66, s40, 0x4000
	v_lshl_add_u64 v[214:215], s[40:41], 0, v[136:137]
	s_addc_u32 s67, s41, 0
	s_add_i32 s63, s75, s16
	global_load_lds_dwordx4 v[214:215], off
	v_lshl_add_u64 v[214:215], s[66:67], 0, v[140:141]
	s_mov_b32 m0, s63
	s_nop 0
	global_load_lds_dwordx4 v[214:215], off
	v_lshl_add_u64 v[214:215], s[66:67], 0, v[136:137]
	s_add_i32 m0, s63, 0x2000
	s_nop 0
	global_load_lds_dwordx4 v[214:215], off
	v_lshl_add_u64 v[214:215], s[42:43], 0, v[142:143]
	s_mov_b32 m0, s19
	s_nop 0
	global_load_lds_dwordx4 v[214:215], off
	v_lshl_add_u64 v[214:215], s[42:43], 0, v[138:139]
	s_mov_b32 m0, s20
	s_nop 0
	global_load_lds_dwordx4 v[214:215], off
	s_waitcnt vmcnt(8)
	s_waitcnt lgkmcnt(0)
	s_barrier
; #define PG8_STAGE(bufoff, gbase, voff) do { _Pragma("unroll") for (int _i = 0; _i < 2; ++_i) \
;         __builtin_amdgcn_global_load_lds((const unsigned*)((const char*)(gbase) + (voff)[_i]), (PG8_LAS unsigned*)(lds + (bufoff) + ldsw + _i * 8192), 16, 0, 0); } while (0)
; #define PG8_LDA(dst, b, h) do { _Pragma("unroll") for (int m = 0; m < 4; ++m) _Pragma("unroll") for (int k = 0; k < 2; ++k) dst[m][k] = *(const PG8_LAS bf16x8*)(lds + PG8_SA(b, h) + aoff + m * 2048 + k * 1024); } while (0)
; #define PG8_LDB(dst, b, h) do { _Pragma("unroll") for (int n = 0; n < 2; ++n) _Pragma("unroll") for (int k = 0; k < 2; ++k) dst[n][k] = *(const PG8_LAS bf16x8*)(lds + PG8_SB(b, h) + boff + n * 2048 + k * 1024); } while (0)
; #define PG8_MMA(ai, bj, At, Bt) do { __builtin_amdgcn_s_setprio(1); _Pragma("unroll") for (int m = 0; m < 4; ++m) _Pragma("unroll") for (int n = 0; n < 2; ++n) _Pragma("unroll") for (int k = 0; k < 2; ++k) \
;         acc[ai][bj][m][n] = __builtin_amdgcn_mfma_f32_16x16x32_bf16(Bt[n][k], At[m][k], acc[ai][bj][m][n], 0, 0, 0); __builtin_amdgcn_s_setprio(0); } while (0)
; #define PG8_WAIT_V(n) asm volatile("s_waitcnt vmcnt(" #n ")" ::: "memory")
; #define PG8_WAIT_L(n) asm volatile("s_waitcnt lgkmcnt(" #n ")" ::: "memory")
; #define PG8_BAR __builtin_amdgcn_s_barrier()
; #define PG8_SCHED __builtin_amdgcn_sched_barrier(0)
; template <class Epi, class Sched, bool ALIGN_EPI = false, bool SP2 = false>
; __device__ __forceinline__ void gemm_phase(PG8_LAS unsigned char* lds, const Gemm g, const Sched& S, const Epi& E) {
;     ...
;             PG8_WAIT_V(8); PG8_WAIT_L(0); PG8_BAR; PG8_MMA(1, 0, At, B0); PG8_MMA(1, 1, At, B1); PG8_BAR; PG8_SCHED;
;             PG8_LDB(B0, 1, 0); PG8_LDB(B1, 1, 1); PG8_SCHED; PG8_LDA(At, 1, 0); PG8_STAGE(PG8_SA(0, 1), a2 + hstepB, voffA);
;             PG8_WAIT_V(8); PG8_WAIT_L(0); PG8_BAR; PG8_MMA(0, 0, At, B0); PG8_MMA(0, 1, At, B1); PG8_BAR; PG8_SCHED;
	s_setprio 1
	s_waitcnt lgkmcnt(0)
	v_mfma_f32_16x16x32_bf16 v[60:63], v[128:131], v[182:185], v[60:63]
	v_mfma_f32_16x16x32_bf16 v[60:63], v[132:135], v[186:189], v[60:63]
	v_mfma_f32_16x16x32_bf16 v[52:55], v[152:155], v[182:185], v[52:55]
	v_mfma_f32_16x16x32_bf16 v[52:55], v[156:159], v[186:189], v[52:55]
	v_mfma_f32_16x16x32_bf16 v[44:47], v[128:131], v[190:193], v[44:47]
	v_mfma_f32_16x16x32_bf16 v[44:47], v[132:135], v[194:197], v[44:47]
	v_mfma_f32_16x16x32_bf16 v[36:39], v[152:155], v[190:193], v[36:39]
	v_mfma_f32_16x16x32_bf16 v[36:39], v[156:159], v[194:197], v[36:39]
	v_mfma_f32_16x16x32_bf16 v[28:31], v[128:131], v[198:201], v[28:31]
	v_mfma_f32_16x16x32_bf16 v[28:31], v[132:135], v[202:205], v[28:31]
	v_mfma_f32_16x16x32_bf16 v[20:23], v[152:155], v[198:201], v[20:23]
	v_mfma_f32_16x16x32_bf16 v[20:23], v[156:159], v[202:205], v[20:23]
	v_mfma_f32_16x16x32_bf16 v[12:15], v[128:131], v[206:209], v[12:15]
	v_mfma_f32_16x16x32_bf16 v[12:15], v[132:135], v[210:213], v[12:15]
	v_mfma_f32_16x16x32_bf16 v[4:7], v[152:155], v[206:209], v[4:7]
	v_mfma_f32_16x16x32_bf16 v[4:7], v[156:159], v[210:213], v[4:7]
	v_mfma_f32_16x16x32_bf16 v[56:59], v[160:163], v[182:185], v[56:59]
	v_mfma_f32_16x16x32_bf16 v[56:59], v[170:173], v[186:189], v[56:59]
	v_mfma_f32_16x16x32_bf16 v[48:51], v[174:177], v[182:185], v[48:51]
	v_mfma_f32_16x16x32_bf16 v[48:51], v[178:181], v[186:189], v[48:51]
	v_mfma_f32_16x16x32_bf16 v[40:43], v[160:163], v[190:193], v[40:43]
	v_mfma_f32_16x16x32_bf16 v[40:43], v[170:173], v[194:197], v[40:43]
	v_mfma_f32_16x16x32_bf16 v[32:35], v[174:177], v[190:193], v[32:35]
	v_mfma_f32_16x16x32_bf16 v[32:35], v[178:181], v[194:197], v[32:35]
	v_mfma_f32_16x16x32_bf16 v[24:27], v[160:163], v[198:201], v[24:27]
	v_mfma_f32_16x16x32_bf16 v[24:27], v[170:173], v[202:205], v[24:27]
	v_mfma_f32_16x16x32_bf16 v[16:19], v[174:177], v[198:201], v[16:19]
	v_mfma_f32_16x16x32_bf16 v[16:19], v[178:181], v[202:205], v[16:19]
	v_mfma_f32_16x16x32_bf16 v[8:11], v[160:163], v[206:209], v[8:11]
	v_mfma_f32_16x16x32_bf16 v[8:11], v[170:173], v[210:213], v[8:11]
	v_mfma_f32_16x16x32_bf16 v[0:3], v[174:177], v[206:209], v[0:3]
	v_mfma_f32_16x16x32_bf16 v[0:3], v[178:181], v[210:213], v[0:3]
	s_setprio 0
	s_barrier
	s_add_i32 s63, 0, 0x18000
	v_add_u32_e32 v151, s63, v165
	s_add_i32 s66, 0, 0x1c000
	ds_read_b128 v[128:131], v151
	ds_read_b128 v[132:135], v151 offset:1024
	ds_read_b128 v[152:155], v151 offset:2048
	ds_read_b128 v[156:159], v151 offset:3072
	v_add_u32_e32 v151, s66, v165
	ds_read_b128 v[160:163], v151
	ds_read_b128 v[170:173], v151 offset:1024
	ds_read_b128 v[174:177], v151 offset:2048
	ds_read_b128 v[178:181], v151 offset:3072
	s_add_u32 s42, s42, 0x4000
	s_addc_u32 s43, s43, 0
	s_mov_b32 m0, s21
	v_lshl_add_u64 v[214:215], s[42:43], 0, v[142:143]
	ds_read_b128 v[182:185], v168 offset:32768
	ds_read_b128 v[186:189], v168 offset:33792
	ds_read_b128 v[190:193], v168 offset:34816
	ds_read_b128 v[194:197], v168 offset:35840
	ds_read_b128 v[198:201], v168 offset:36864
	ds_read_b128 v[202:205], v168 offset:37888
	ds_read_b128 v[206:209], v168 offset:38912
	ds_read_b128 v[210:213], v168 offset:39936
	global_load_lds_dwordx4 v[214:215], off
	v_lshl_add_u64 v[214:215], s[42:43], 0, v[138:139]
	s_mov_b32 m0, s22
	s_nop 0
	global_load_lds_dwordx4 v[214:215], off
	s_waitcnt vmcnt(8)
	s_waitcnt lgkmcnt(0)
	s_barrier
	s_setprio 1
	s_waitcnt lgkmcnt(0)
	v_mfma_f32_16x16x32_bf16 v[124:127], v[128:131], v[182:185], v[124:127]
	v_mfma_f32_16x16x32_bf16 v[124:127], v[132:135], v[186:189], v[124:127]
	v_mfma_f32_16x16x32_bf16 v[116:119], v[152:155], v[182:185], v[116:119]
	v_mfma_f32_16x16x32_bf16 v[116:119], v[156:159], v[186:189], v[116:119]
	v_mfma_f32_16x16x32_bf16 v[108:111], v[128:131], v[190:193], v[108:111]
	v_mfma_f32_16x16x32_bf16 v[108:111], v[132:135], v[194:197], v[108:111]
	v_mfma_f32_16x16x32_bf16 v[100:103], v[152:155], v[190:193], v[100:103]
	v_mfma_f32_16x16x32_bf16 v[100:103], v[156:159], v[194:197], v[100:103]
	v_mfma_f32_16x16x32_bf16 v[92:95], v[128:131], v[198:201], v[92:95]
	v_mfma_f32_16x16x32_bf16 v[92:95], v[132:135], v[202:205], v[92:95]
	v_mfma_f32_16x16x32_bf16 v[84:87], v[152:155], v[198:201], v[84:87]
	v_mfma_f32_16x16x32_bf16 v[84:87], v[156:159], v[202:205], v[84:87]
	v_mfma_f32_16x16x32_bf16 v[76:79], v[128:131], v[206:209], v[76:79]
	v_mfma_f32_16x16x32_bf16 v[76:79], v[132:135], v[210:213], v[76:79]
	v_mfma_f32_16x16x32_bf16 v[68:71], v[152:155], v[206:209], v[68:71]
	v_mfma_f32_16x16x32_bf16 v[68:71], v[156:159], v[210:213], v[68:71]
	v_mfma_f32_16x16x32_bf16 v[120:123], v[160:163], v[182:185], v[120:123]
	v_mfma_f32_16x16x32_bf16 v[120:123], v[170:173], v[186:189], v[120:123]
	v_mfma_f32_16x16x32_bf16 v[112:115], v[174:177], v[182:185], v[112:115]
	v_mfma_f32_16x16x32_bf16 v[112:115], v[178:181], v[186:189], v[112:115]
	v_mfma_f32_16x16x32_bf16 v[104:107], v[160:163], v[190:193], v[104:107]
	v_mfma_f32_16x16x32_bf16 v[104:107], v[170:173], v[194:197], v[104:107]
	v_mfma_f32_16x16x32_bf16 v[96:99], v[174:177], v[190:193], v[96:99]
	v_mfma_f32_16x16x32_bf16 v[96:99], v[178:181], v[194:197], v[96:99]
	v_mfma_f32_16x16x32_bf16 v[88:91], v[160:163], v[198:201], v[88:91]
	v_mfma_f32_16x16x32_bf16 v[88:91], v[170:173], v[202:205], v[88:91]
	v_mfma_f32_16x16x32_bf16 v[80:83], v[174:177], v[198:201], v[80:83]
	v_mfma_f32_16x16x32_bf16 v[80:83], v[178:181], v[202:205], v[80:83]
	v_mfma_f32_16x16x32_bf16 v[72:75], v[160:163], v[206:209], v[72:75]
	v_mfma_f32_16x16x32_bf16 v[72:75], v[170:173], v[210:213], v[72:75]
	v_mfma_f32_16x16x32_bf16 v[64:67], v[174:177], v[206:209], v[64:67]
	v_mfma_f32_16x16x32_bf16 v[64:67], v[178:181], v[210:213], v[64:67]
	s_setprio 0
	s_barrier
; #define PG8_STAGE(bufoff, gbase, voff) do { _Pragma("unroll") for (int _i = 0; _i < 2; ++_i) \
;         __builtin_amdgcn_global_load_lds((const unsigned*)((const char*)(gbase) + (voff)[_i]), (PG8_LAS unsigned*)(lds + (bufoff) + ldsw + _i * 8192), 16, 0, 0); } while (0)
; #define PG8_LDA(dst, b, h) do { _Pragma("unroll") for (int m = 0; m < 4; ++m) _Pragma("unroll") for (int k = 0; k < 2; ++k) dst[m][k] = *(const PG8_LAS bf16x8*)(lds + PG8_SA(b, h) + aoff + m * 2048 + k * 1024); } while (0)
; #define PG8_MMA(ai, bj, At, Bt) do { __builtin_amdgcn_s_setprio(1); _Pragma("unroll") for (int m = 0; m < 4; ++m) _Pragma("unroll") for (int n = 0; n < 2; ++n) _Pragma("unroll") for (int k = 0; k < 2; ++k) \
;         acc[ai][bj][m][n] = __builtin_amdgcn_mfma_f32_16x16x32_bf16(Bt[n][k], At[m][k], acc[ai][bj][m][n], 0, 0, 0); __builtin_amdgcn_s_setprio(0); } while (0)
; #define PG8_WAIT_V(n) asm volatile("s_waitcnt vmcnt(" #n ")" ::: "memory")
; #define PG8_WAIT_L(n) asm volatile("s_waitcnt lgkmcnt(" #n ")" ::: "memory")
; #define PG8_BAR __builtin_amdgcn_s_barrier()
; #define PG8_SCHED __builtin_amdgcn_sched_barrier(0)
; template <class Epi, class Sched, bool ALIGN_EPI = false, bool SP2 = false>
; __device__ __forceinline__ void gemm_phase(PG8_LAS unsigned char* lds, const Gemm g, const Sched& S, const Epi& E) {
;     ...
;         for (int t = 0; t < nt; t += 2) {
;             const bool last = (t == nt - 2);
;     ...
;             PG8_LDA(At, 1, 1); PG8_STAGE(PG8_SB(1, 0), b3, voffB); PG8_STAGE(PG8_SB(1, 1), b3 + hstepB, voffB); PG8_STAGE(PG8_SA(1, 0), a3, voffA);
;             PG8_WAIT_V(8); PG8_WAIT_L(0); PG8_BAR; PG8_MMA(1, 0, At, B0); PG8_MMA(1, 1, At, B1); PG8_BAR; PG8_SCHED;
	s_add_u32 s42, s40, 0x8000
	s_addc_u32 s43, s41, 0
	s_add_i32 s63, s63, s16
	v_lshl_add_u64 v[214:215], s[42:43], 0, v[140:141]
	s_mov_b32 m0, s63
	ds_read_b128 v[182:185], v168 offset:49152
	ds_read_b128 v[186:189], v168 offset:50176
	ds_read_b128 v[190:193], v168 offset:51200
	ds_read_b128 v[194:197], v168 offset:52224
	ds_read_b128 v[198:201], v168 offset:53248
	ds_read_b128 v[202:205], v168 offset:54272
	ds_read_b128 v[206:209], v168 offset:55296
	ds_read_b128 v[210:213], v168 offset:56320
	global_load_lds_dwordx4 v[214:215], off
	s_add_i32 m0, s63, 0x2000
	s_add_u32 s40, s40, 0xc000
	v_lshl_add_u64 v[214:215], s[42:43], 0, v[136:137]
	s_addc_u32 s41, s41, 0
	s_add_i32 s42, s66, s16
	global_load_lds_dwordx4 v[214:215], off
	v_lshl_add_u64 v[214:215], s[40:41], 0, v[140:141]
	s_mov_b32 m0, s42
	s_nop 0
	global_load_lds_dwordx4 v[214:215], off
	v_lshl_add_u64 v[214:215], s[40:41], 0, v[136:137]
	s_add_i32 m0, s42, 0x2000
	s_nop 0
	global_load_lds_dwordx4 v[214:215], off
	v_lshl_add_u64 v[214:215], s[38:39], 0, v[142:143]
	s_mov_b32 m0, s25
	s_nop 0
	global_load_lds_dwordx4 v[214:215], off
	v_lshl_add_u64 v[214:215], s[38:39], 0, v[138:139]
	s_mov_b32 m0, s26
	s_nop 0
	global_load_lds_dwordx4 v[214:215], off
	s_waitcnt vmcnt(8)
	s_waitcnt lgkmcnt(0)
	s_barrier
	s_setprio 1
	s_waitcnt lgkmcnt(0)
	v_mfma_f32_16x16x32_bf16 v[60:63], v[128:131], v[182:185], v[60:63]
	v_mfma_f32_16x16x32_bf16 v[60:63], v[132:135], v[186:189], v[60:63]
	v_mfma_f32_16x16x32_bf16 v[52:55], v[152:155], v[182:185], v[52:55]
	v_mfma_f32_16x16x32_bf16 v[52:55], v[156:159], v[186:189], v[52:55]
	v_mfma_f32_16x16x32_bf16 v[44:47], v[128:131], v[190:193], v[44:47]
	v_mfma_f32_16x16x32_bf16 v[44:47], v[132:135], v[194:197], v[44:47]
	v_mfma_f32_16x16x32_bf16 v[36:39], v[152:155], v[190:193], v[36:39]
	v_mfma_f32_16x16x32_bf16 v[36:39], v[156:159], v[194:197], v[36:39]
	v_mfma_f32_16x16x32_bf16 v[28:31], v[128:131], v[198:201], v[28:31]
	v_mfma_f32_16x16x32_bf16 v[28:31], v[132:135], v[202:205], v[28:31]
	v_mfma_f32_16x16x32_bf16 v[20:23], v[152:155], v[198:201], v[20:23]
	v_mfma_f32_16x16x32_bf16 v[20:23], v[156:159], v[202:205], v[20:23]
	v_mfma_f32_16x16x32_bf16 v[12:15], v[128:131], v[206:209], v[12:15]
	v_mfma_f32_16x16x32_bf16 v[12:15], v[132:135], v[210:213], v[12:15]
	v_mfma_f32_16x16x32_bf16 v[4:7], v[152:155], v[206:209], v[4:7]
	v_mfma_f32_16x16x32_bf16 v[4:7], v[156:159], v[210:213], v[4:7]
	v_mfma_f32_16x16x32_bf16 v[56:59], v[160:163], v[182:185], v[56:59]
	v_mfma_f32_16x16x32_bf16 v[56:59], v[170:173], v[186:189], v[56:59]
	v_mfma_f32_16x16x32_bf16 v[48:51], v[174:177], v[182:185], v[48:51]
	v_mfma_f32_16x16x32_bf16 v[48:51], v[178:181], v[186:189], v[48:51]
	v_mfma_f32_16x16x32_bf16 v[40:43], v[160:163], v[190:193], v[40:43]
	v_mfma_f32_16x16x32_bf16 v[40:43], v[170:173], v[194:197], v[40:43]
	v_mfma_f32_16x16x32_bf16 v[32:35], v[174:177], v[190:193], v[32:35]
	v_mfma_f32_16x16x32_bf16 v[32:35], v[178:181], v[194:197], v[32:35]
	v_mfma_f32_16x16x32_bf16 v[24:27], v[160:163], v[198:201], v[24:27]
	v_mfma_f32_16x16x32_bf16 v[24:27], v[170:173], v[202:205], v[24:27]
	v_mfma_f32_16x16x32_bf16 v[16:19], v[174:177], v[198:201], v[16:19]
	v_mfma_f32_16x16x32_bf16 v[16:19], v[178:181], v[202:205], v[16:19]
	v_mfma_f32_16x16x32_bf16 v[8:11], v[160:163], v[206:209], v[8:11]
	v_mfma_f32_16x16x32_bf16 v[8:11], v[170:173], v[210:213], v[8:11]
	v_mfma_f32_16x16x32_bf16 v[0:3], v[174:177], v[206:209], v[0:3]
	v_mfma_f32_16x16x32_bf16 v[0:3], v[178:181], v[210:213], v[0:3]
	s_setprio 0
	s_barrier
	s_add_i32 s62, s62, 2
	s_add_u32 s36, s36, 0x10000
	s_addc_u32 s37, s37, 0
	s_add_u32 s44, s44, 0x10000
	s_addc_u32 s45, s45, 0
	s_cmp_gt_u32 s62, 29
	s_cbranch_scc0 .LBB0_263
	s_and_b64 vcc, exec, s[8:9]
	s_cbranch_vccz .LBB0_266
	s_barrier
